# v21 + split-phase barrier 2: late (pass-B) workgroups arrive at grid barrier 2 without spinning, run their pass-B unit, and do the generation check + acquire just before phase 3
# speedup vs baseline: 1.0811x; 1.0200x over previous
; __device__ __forceinline__ unsigned xb_ld(unsigned* p)              { return __hip_atomic_load(p, __ATOMIC_RELAXED, __HIP_MEMORY_SCOPE_AGENT); }
; #define XB_SPIN(cond, bar) do { unsigned _sp = 0; while (cond) { __builtin_amdgcn_s_sleep(XB_SLEEP); \
;     if ((++_sp & 255u) == 0u) { if (xb_ld(&(bar)[XB_TMO])) break; if (_sp > XB_SPIN_CAP) { atomicAdd(&(bar)[XB_TMO], 1u); break; } } } } while (0)
; #define STAMP() do { if (PROBE_SEG >= 0 && bx == 0 && tid == 0) { tst[nst] = __builtin_amdgcn_s_memrealtime(); } ++nst; } while (0)
; #define BOTH(k) (IN(k) && IN((k) + 1))
; __device__ __forceinline__ void xcd_barrier(const XcdBarrier& b) {
;     ...
;         } else {
;             XB_SPIN(xb_ld(&bar[XB_XGEN(b.x)]) == gen, bar);
;             __builtin_amdgcn_fence(__ATOMIC_ACQUIRE, "agent");
;             asm volatile("s_waitcnt vmcnt(0)" ::: "memory");
;         }
; __global__ void __launch_bounds__(512, 2) hymba_fwd(Params p) {
;     ...
;         if (BOTH(1)) GBAR(); STAMP();
.LBB0_576:
	s_cmp_eq_u32 s98, 1
	s_cbranch_scc0 .Lp1_bar
	s_mov_b32 s98, 2
	s_waitcnt vmcnt(0) lgkmcnt(0)
	v_readlane_b32 s0, v254, 9
	s_cmpk_gt_i32 s0, 0x93
	s_cbranch_scc1 .Lb2w_skip
	v_cmp_eq_u32_e32 vcc, 0, v0
	s_and_saveexec_b64 s[0:1], vcc
	s_cbranch_execz .Lb2w_done
	v_readlane_b32 s2, v254, 7
	s_lshl_b32 s2, s2, 8
	v_readlane_b32 s4, v254, 5
	v_readlane_b32 s5, v254, 6
	s_add_u32 s2, s4, s2
	s_addc_u32 s3, s5, 0
	s_mov_b32 s5, 0x8000
	v_mov_b32_e32 v1, 0x2400
.Lb2w_poll:
	global_load_dword v2, v1, s[2:3] sc1
	s_waitcnt vmcnt(0)
	v_readfirstlane_b32 s4, v2
	s_cmp_ge_u32 s4, 2
	s_cbranch_scc1 .Lb2w_ok
	s_add_i32 s5, s5, -1
	s_cmp_eq_u32 s5, 0
	s_cbranch_scc1 .Lb2w_ok
	s_sleep 1
	s_branch .Lb2w_poll

; #define STAMP() do { if (PROBE_SEG >= 0 && bx == 0 && tid == 0) { tst[nst] = __builtin_amdgcn_s_memrealtime(); } ++nst; } while (0)
; #define BOTH(k) (IN(k) && IN((k) + 1))
; __global__ void __launch_bounds__(512, 2) hymba_fwd(Params p) {
;     ...
;         if (BOTH(1)) GBAR(); STAMP();
;     }
;     if (IN(3)) { phase3<31>(p, lds, ctlw, 0); if (BOTH(3)) GBAR(); STAMP(); }
.Lb2w_skip:
	s_barrier
	v_readlane_b32 s6, v254, 3
	v_readlane_b32 s7, v254, 4
	s_branch .LBB0_626

; __device__ __forceinline__ unsigned xb_ld(unsigned* p)              { return __hip_atomic_load(p, __ATOMIC_RELAXED, __HIP_MEMORY_SCOPE_AGENT); }
; __device__ __forceinline__ unsigned xb_add(unsigned* p, unsigned v) { return __hip_atomic_fetch_add(p, v, __ATOMIC_RELAXED, __HIP_MEMORY_SCOPE_AGENT); }
; #define XB_SPIN(cond, bar) do { unsigned _sp = 0; while (cond) { __builtin_amdgcn_s_sleep(XB_SLEEP); \
;     if ((++_sp & 255u) == 0u) { if (xb_ld(&(bar)[XB_TMO])) break; if (_sp > XB_SPIN_CAP) { atomicAdd(&(bar)[XB_TMO], 1u); break; } } } } while (0)
; __device__ __forceinline__ void xcd_barrier(const XcdBarrier& b) {
;     ...
;         const unsigned old = xb_add(&bar[XB_XSUB(b.x)], 1u);
;         const unsigned gen = old / nloc;
;         if (old + 1u == (gen + 1u) * nloc) {
;             __builtin_amdgcn_fence(__ATOMIC_RELEASE, "agent");
;             asm volatile("s_waitcnt vmcnt(0)" ::: "memory");
;             const unsigned og = xb_add(&bar[XB_TOP], 1u);
;             const unsigned tg = og / nx;
;             if (og + 1u == (tg + 1u) * nx) xb_add(&bar[XB_TOPGEN], 1u);
;             else XB_SPIN(xb_ld(&bar[XB_TOPGEN]) == tg, bar);
;             __builtin_amdgcn_fence(__ATOMIC_ACQUIRE, "agent");
;             xb_add(&bar[XB_XGEN(b.x)], 1u);
;             asm volatile("s_waitcnt vmcnt(0)" ::: "memory");
;         } else {
;             XB_SPIN(xb_ld(&bar[XB_XGEN(b.x)]) == gen, bar);
;             __builtin_amdgcn_fence(__ATOMIC_ACQUIRE, "agent");
;             asm volatile("s_waitcnt vmcnt(0)" ::: "memory");
;         }
.LBB0_593:
	v_readlane_b32 s2, v254, 7
	s_lshl_b32 s2, s2, 8
	v_readlane_b32 s4, v254, 5
	v_readlane_b32 s5, v254, 6
	s_add_u32 s2, s4, s2
	s_addc_u32 s3, s5, 0
	v_mov_b32_e32 v2, 0x1000
	v_mov_b32_e32 v4, 1
	global_atomic_add v4, v2, v4, s[2:3] offset:1024 sc0
	v_cvt_f32_u32_e32 v2, v3
	v_sub_u32_e32 v5, 0, v3
	v_rcp_iflag_f32_e32 v2, v2
	s_nop 0
	v_mul_f32_e32 v2, 0x4f7ffffe, v2
	v_cvt_u32_f32_e32 v2, v2
	v_mul_lo_u32 v5, v5, v2
	v_mul_hi_u32 v5, v2, v5
	v_add_u32_e32 v2, v2, v5
	s_waitcnt vmcnt(0)
	v_mul_hi_u32 v2, v4, v2
	v_mul_lo_u32 v5, v2, v3
	v_sub_u32_e32 v5, v4, v5
	v_add_u32_e32 v6, 1, v2
	v_cmp_ge_u32_e32 vcc, v5, v3
	v_add_u32_e32 v4, 1, v4
	s_nop 0
	v_cndmask_b32_e32 v2, v2, v6, vcc
	v_sub_u32_e32 v6, v5, v3
	v_cndmask_b32_e32 v5, v5, v6, vcc
	v_add_u32_e32 v6, 1, v2
	v_cmp_ge_u32_e32 vcc, v5, v3
	s_nop 1
	v_cndmask_b32_e32 v2, v2, v6, vcc
	v_mul_lo_u32 v5, v3, v2
	v_add_u32_e32 v3, v5, v3
	v_cmp_ne_u32_e32 vcc, v4, v3
	s_and_saveexec_b64 s[4:5], vcc
	s_xor_b64 s[4:5], exec, s[4:5]
	s_cbranch_execz .LBB0_607
	v_readlane_b32 s10, v254, 9
	s_cmpk_lt_i32 s10, 0x94
	s_cbranch_scc1 .LBB0_607
	s_waitcnt lgkmcnt(0)
	v_mov_b32_e32 v1, 0x2000
	global_load_dword v1, v1, s[2:3] offset:1024 sc1
	s_add_u32 s10, s2, 0x2400
	s_addc_u32 s11, s3, 0
	s_waitcnt vmcnt(0)
	v_cmp_eq_u32_e32 vcc, v1, v2
	s_and_saveexec_b64 s[6:7], vcc
	s_cbranch_execz .LBB0_606
	s_add_u32 s8, s90, 0x4200
	s_addc_u32 s9, s91, 0
	s_mov_b32 s22, 1
	s_mov_b64 s[12:13], 0
	v_mov_b32_e32 v1, 0
	s_branch .LBB0_597
